# phase E tile prologue: 16 residual loads from one tile-uniform base pointer plus lane offset (replaces 16 copies of the per-lane source selection)
# speedup vs baseline: 1.0135x; 1.0091x over previous
; DI void phaseE_tile(const P& p, int layer, int mt, int nt, char* lds) {
;     ...
;   float* XF = p.out;
;   const int col = col0 + wn * 64 + fr * 4;
;   f32x4 xr[16];
; #pragma unroll
;   for (int ps = 0; ps < 16; ++ps) {
;     const int row = row0 + ps * 8 + wm * 4 + fq;
;     const float* xin = (layer == 0) ? ((row < NTP) ? p.x_p + (size_t)row * DM : p.x_s + (size_t)(row - NTP) * DM) : XF + (size_t)row * DM;
;     xr[ps] = __builtin_nontemporal_load((const f32x4*)(xin + col));
;   }
.LBB0_41:
	s_lshl_b32 s10, s17, 7
	v_readfirstlane_b32 s19, v158
	v_bfe_u32 v142, v158, 4, 2
	v_and_b32_e32 v143, 15, v158
	s_lshl_b32 s22, s18, 7
	s_ashr_i32 s20, s19, 7
	s_bfe_u32 s19, s19, 0x10006
	s_lshl_b32 s11, s20, 2
	s_lshl_b32 s21, s19, 6
	v_lshlrev_b32_e32 v144, 2, v143
	v_or_b32_e32 v0, s22, v144
	v_or_b32_e32 v130, s21, v0
	v_mov_b32_e32 v131, 0
	v_cndmask_b32_e64 v0, 0, 1, s[2:3]
	v_cmp_ne_u32_e64 s[38:39], 1, v0
	s_mov_b64 s[36:37], s[88:89]
	s_mov_b32 s8, s10
	s_and_b64 vcc, exec, s[2:3]
	s_cbranch_vccnz .Lxr_go
	v_readlane_b32 s36, v240, 6
	v_readlane_b32 s37, v240, 7
	s_cmp_lt_i32 s10, 0x8000
	s_cbranch_scc1 .Lxr_go
	v_readlane_b32 s36, v240, 8
	v_readlane_b32 s37, v240, 9
	s_add_i32 s8, s10, 0xffff8000
.Lxr_go:
	s_add_i32 s8, s8, s11
	s_lshl_b32 s9, s8, 12
	v_lshlrev_b32_e32 v0, 12, v142
	s_add_u32 s36, s36, s9
	s_addc_u32 s37, s37, 0
	v_lshl_add_u32 v0, v130, 2, v0
	global_load_dwordx4 v[2:5], v0, s[36:37] nt
	s_add_u32 s36, s36, 0x8000
	s_addc_u32 s37, s37, 0
	global_load_dwordx4 v[6:9], v0, s[36:37] nt
	s_add_u32 s36, s36, 0x8000
	s_addc_u32 s37, s37, 0
	global_load_dwordx4 v[10:13], v0, s[36:37] nt
	s_add_u32 s36, s36, 0x8000
	s_addc_u32 s37, s37, 0
	global_load_dwordx4 v[14:17], v0, s[36:37] nt
	s_add_u32 s36, s36, 0x8000
	s_addc_u32 s37, s37, 0
	global_load_dwordx4 v[18:21], v0, s[36:37] nt
	s_add_u32 s36, s36, 0x8000
	s_addc_u32 s37, s37, 0
	global_load_dwordx4 v[22:25], v0, s[36:37] nt
	s_add_u32 s36, s36, 0x8000
	s_addc_u32 s37, s37, 0
	global_load_dwordx4 v[26:29], v0, s[36:37] nt
	s_add_u32 s36, s36, 0x8000
	s_addc_u32 s37, s37, 0
	global_load_dwordx4 v[30:33], v0, s[36:37] nt
	s_add_u32 s36, s36, 0x8000
	s_addc_u32 s37, s37, 0
	global_load_dwordx4 v[34:37], v0, s[36:37] nt
	s_add_u32 s36, s36, 0x8000
	s_addc_u32 s37, s37, 0
	global_load_dwordx4 v[38:41], v0, s[36:37] nt
	s_add_u32 s36, s36, 0x8000
	s_addc_u32 s37, s37, 0
	global_load_dwordx4 v[42:45], v0, s[36:37] nt
	s_add_u32 s36, s36, 0x8000
	s_addc_u32 s37, s37, 0
	global_load_dwordx4 v[46:49], v0, s[36:37] nt
	s_add_u32 s36, s36, 0x8000
	s_addc_u32 s37, s37, 0
	global_load_dwordx4 v[50:53], v0, s[36:37] nt
	s_add_u32 s36, s36, 0x8000
	s_addc_u32 s37, s37, 0
	global_load_dwordx4 v[54:57], v0, s[36:37] nt
	s_add_u32 s36, s36, 0x8000
	s_addc_u32 s37, s37, 0
	global_load_dwordx4 v[58:61], v0, s[36:37] nt
	s_add_u32 s36, s36, 0x8000
	s_addc_u32 s37, s37, 0
	global_load_dwordx4 v[62:65], v0, s[36:37] nt
; DI void gemm_tile(const bf16_t* __restrict__ A, int lda, const bf16_t* __restrict__ Bt, int ldb, int bvalid, int K, f32x4 (&acc)[4][4], char* lds, bool preloaded = false) {
;     ...
;   const bf16_t* ap = A + (size_t)lr * lda + ((lc ^ ((lr >> 1) & 7)) << 3);
;   const bf16_t* bp = Bt + ((lc ^ ((lr >> 1) & 7)) << 3);
;   typedef __attribute__((address_space(1))) const unsigned gptr_t;
;   typedef __attribute__((address_space(3))) unsigned lptr_t;
;   const unsigned lbase = (unsigned)(size_t)lds + (unsigned)tid * 16u;
; DI void phaseE_tile(const P& p, int layer, int mt, int nt, char* lds) {
;     ...
;     xr[ps] = __builtin_nontemporal_load((const f32x4*)(xin + col));
;   }
;   gemm_tile((const bf16_t*)(p.ws + W_MERGED) + (size_t)row0 * LDX, LDX, (const bf16_t*)(p.ws + W_WO) + ((size_t)layer * 1024 + col0) * LDX, LDX, 128, 1024, acc, lds);
.LBB0_169:
	s_mul_i32 s8, s10, 0x880
	s_mul_hi_i32 s9, s10, 0x880
	s_add_u32 s24, s58, s8
	s_addc_u32 s25, s59, s9
	s_ashr_i32 s23, s22, 31
	s_add_u32 s26, s4, s22
	s_addc_u32 s23, s5, s23
	v_mov_b32_e32 v76, v158
	s_mulk_i32 s23, 0x880
	s_mul_hi_u32 s27, s26, 0x880
	s_add_i32 s27, s27, s23
	v_lshrrev_b32_e32 v78, 4, v76
	s_mulk_i32 s26, 0x880
	v_readlane_b32 s28, v240, 31
	v_xor_b32_e32 v0, v78, v76
	v_readlane_b32 s29, v240, 32
	s_add_u32 s26, s28, s26
	v_ashrrev_i32_e32 v77, 3, v76
	v_mov_b64_e32 v[66:67], s[24:25]
	s_movk_i32 s28, 0x880
	v_lshlrev_b32_e32 v0, 4, v0
	s_addc_u32 s27, s29, s27
	v_mad_i64_i32 v[66:67], s[24:25], v77, s28, v[66:67]
	v_and_b32_e32 v0, 0x70, v0
	v_lshl_add_u64 v[66:67], v[66:67], 0, v[0:1]
	v_lshl_add_u64 v[68:69], s[26:27], 0, v[0:1]
	v_lshlrev_b32_e32 v145, 4, v76
	v_and_b32_e32 v0, 0x7f, v77
	v_add_u32_e32 v72, 0x4000, v145
	v_readfirstlane_b32 s24, v145
	v_mul_u32_u24_e32 v0, 0x440, v0
	s_mov_b32 m0, s24
	v_lshlrev_b32_e32 v0, 1, v0
	v_readfirstlane_b32 s24, v72
	global_load_lds_dwordx4 v[66:67], off
	v_lshl_add_u64 v[70:71], v[68:69], 0, v[0:1]
	s_mov_b32 m0, s24
	s_mov_b64 s[24:25], 0x11000
	v_add_u32_e32 v72, 0x1000, v145
	global_load_lds_dwordx4 v[70:71], off
	v_lshl_add_u64 v[70:71], v[66:67], 0, s[24:25]
	v_readfirstlane_b32 s24, v72
	s_mov_b32 m0, s24
	v_add_u32_e32 v74, 0x5000, v145
	global_load_lds_dwordx4 v[70:71], off
	v_add_u32_e32 v70, 32, v77
	v_and_b32_e32 v70, 0x7f, v70
	v_mul_u32_u24_e32 v70, 0x440, v70
	v_lshlrev_b32_e32 v70, 1, v70
	v_mov_b32_e32 v71, v1
	v_readfirstlane_b32 s24, v74
	v_lshl_add_u64 v[72:73], v[68:69], 0, v[70:71]
	s_mov_b32 m0, s24
	s_mov_b64 s[24:25], 0x22000
	v_add_u32_e32 v74, 0x2000, v145
	global_load_lds_dwordx4 v[72:73], off
	v_lshl_add_u64 v[72:73], v[66:67], 0, s[24:25]
	v_readfirstlane_b32 s24, v74
	s_mov_b32 m0, s24
	v_add_u32_e32 v82, 0x6000, v145
	global_load_lds_dwordx4 v[72:73], off
	v_bitop3_b32 v72, v77, 64, v166 bitop3:0x6c
	v_mul_u32_u24_e32 v72, 0x440, v72
	v_lshlrev_b32_e32 v72, 1, v72
	v_mov_b32_e32 v73, v1
	v_readfirstlane_b32 s24, v82
	v_lshl_add_u64 v[74:75], v[68:69], 0, v[72:73]
	s_mov_b32 m0, s24
	s_mov_b64 s[24:25], 0x33000
	global_load_lds_dwordx4 v[74:75], off
	v_add_u32_e32 v74, 0x3000, v145
	v_lshl_add_u64 v[66:67], v[66:67], 0, s[24:25]
	v_readfirstlane_b32 s24, v74
	s_mov_b32 m0, s24
	v_add_u32_e32 v74, 0x7000, v145
	global_load_lds_dwordx4 v[66:67], off
	v_add_u32_e32 v66, 0x60, v77
	v_and_b32_e32 v66, 0x7f, v66
	v_mul_u32_u24_e32 v66, 0x440, v66
	v_lshlrev_b32_e32 v66, 1, v66
	v_mov_b32_e32 v67, v1
	v_readfirstlane_b32 s24, v74
	v_lshl_add_u64 v[68:69], v[68:69], 0, v[66:67]
	s_mov_b32 m0, s24
	v_readfirstlane_b32 s23, v76
	global_load_lds_dwordx4 v[68:69], off
	s_lshl_b32 s24, s23, 7
	v_lshlrev_b32_e32 v68, 7, v76
	s_lshl_b32 s23, s23, 6
	v_bfe_u32 v79, v76, 4, 2
	v_lshrrev_b32_e32 v80, 1, v76
	v_bfe_u32 v81, v76, 1, 3
	s_and_b32 s24, s24, 0x2000
	v_and_b32_e32 v68, 0x780, v68
	s_and_b32 s23, s23, 0xffffe000
	v_or_b32_e32 v146, s24, v68
	v_bitop3_b32 v69, v80, v79, 7 bitop3:0x6c
	v_or_b32_e32 v148, s23, v68
	v_bitop3_b32 v68, v79, v81, 4 bitop3:0x36
	v_lshlrev_b32_e32 v149, 4, v69
	v_lshlrev_b32_e32 v147, 4, v68
	v_mov_b64_e32 v[68:69], s[8:9]
	v_bitop3_b32 v74, v78, 7, v76 bitop3:0x48
	v_mad_i64_i32 v[68:69], s[8:9], v77, s28, v[68:69]
	v_lshlrev_b32_e32 v74, 4, v74
	v_or_b32_e32 v68, v68, v74
	s_mul_hi_i32 s8, s22, 0x880
	s_mulk_i32 s22, 0x880
	v_lshl_add_u64 v[132:133], s[90:91], 0, v[68:69]
	v_or_b32_e32 v68, s22, v74
	v_mov_b32_e32 v69, s8
	v_lshl_add_u64 v[70:71], v[68:69], 0, v[70:71]
	v_lshl_add_u64 v[66:67], v[68:69], 0, v[66:67]
	v_lshl_add_u64 v[74:75], v[68:69], 0, v[0:1]
	v_lshl_add_u64 v[136:137], s[6:7], 0, v[70:71]
	v_lshl_add_u64 v[70:71], v[68:69], 0, v[72:73]
	v_lshl_add_u64 v[140:141], s[6:7], 0, v[66:67]
	v_mov_b32_e32 v66, 0
	v_lshl_add_u64 v[134:135], s[6:7], 0, v[74:75]
	v_lshl_add_u64 v[138:139], s[6:7], 0, v[70:71]
	s_mov_b64 s[8:9], 0
	s_mov_b32 s22, 0
	v_mov_b32_e32 v67, v66
	v_mov_b32_e32 v68, v66
	v_mov_b32_e32 v69, v66
	v_mov_b32_e32 v70, v66
	v_mov_b32_e32 v71, v66
	v_mov_b32_e32 v72, v66
	v_mov_b32_e32 v73, v66
	v_mov_b32_e32 v74, v66
	v_mov_b32_e32 v75, v66
	v_mov_b32_e32 v76, v66
	v_mov_b32_e32 v77, v66
	v_mov_b32_e32 v78, v66
	v_mov_b32_e32 v79, v66
	v_mov_b32_e32 v80, v66
	v_mov_b32_e32 v81, v66
	v_mov_b32_e32 v82, v66
	v_mov_b32_e32 v83, v66
	v_mov_b32_e32 v84, v66
	v_mov_b32_e32 v85, v66
	v_mov_b32_e32 v86, v66
	v_mov_b32_e32 v87, v66
	v_mov_b32_e32 v88, v66
	v_mov_b32_e32 v89, v66
	v_mov_b32_e32 v90, v66
	v_mov_b32_e32 v91, v66
	v_mov_b32_e32 v92, v66
	v_mov_b32_e32 v93, v66
	v_mov_b32_e32 v94, v66
	v_mov_b32_e32 v95, v66
	v_mov_b32_e32 v96, v66
	v_mov_b32_e32 v97, v66
	v_mov_b32_e32 v98, v66
	v_mov_b32_e32 v99, v66
	v_mov_b32_e32 v100, v66
	v_mov_b32_e32 v101, v66
	v_mov_b32_e32 v102, v66
	v_mov_b32_e32 v103, v66
	v_mov_b32_e32 v104, v66
	v_mov_b32_e32 v105, v66
	v_mov_b32_e32 v106, v66
	v_mov_b32_e32 v107, v66
	v_mov_b32_e32 v108, v66
	v_mov_b32_e32 v109, v66
	v_mov_b32_e32 v110, v66
	v_mov_b32_e32 v111, v66
	v_mov_b32_e32 v112, v66
	v_mov_b32_e32 v113, v66
	v_mov_b32_e32 v114, v66
	v_mov_b32_e32 v115, v66
	v_mov_b32_e32 v116, v66
	v_mov_b32_e32 v117, v66
	v_mov_b32_e32 v118, v66
	v_mov_b32_e32 v119, v66
	v_mov_b32_e32 v120, v66
	v_mov_b32_e32 v121, v66
	v_mov_b32_e32 v122, v66
	v_mov_b32_e32 v123, v66
	v_mov_b32_e32 v124, v66
	v_mov_b32_e32 v125, v66
	v_mov_b32_e32 v126, v66
	v_mov_b32_e32 v127, v66
	v_mov_b32_e32 v128, v66
	v_mov_b32_e32 v129, v66
	s_waitcnt vmcnt(0) lgkmcnt(0)
	s_barrier
	.p2alignl 6, 3212836864
